# decode step: value/gate/gain small loads issued at unit top ahead of the state tile; tail no longer waits on memory
# speedup vs baseline: 1.0073x; 1.0073x over previous
; __device__ __forceinline__ bf16_t f2bf(float f) { return (bf16_t)(cvt_pk_bf16(f, 0.f) & 0xffffu); }
; __device__ __forceinline__ float silu_f(float x) { return x * __builtin_amdgcn_rcpf(1.f + __expf(-x)); }
; __device__ __forceinline__ float logsig_f(float z) { return fminf(z, 0.f) - __logf(1.f + __expf(-fabsf(z))); }
; template <bool WITH_O> __device__ __forceinline__ void gla_sample(LAS unsigned char* lds, int uidx, const float* PRS, const float* GLRP, const float* w2, const float* gb, const float* gn, ...
;     ...
;     const size_t sb = ((size_t)(s * 4 + h) * DK) * DV + (tid & 63) * 4; f32x4 S[16];
; #pragma unroll
;     for (int kk = 0; kk < 16; ++kk) S[kk] = __builtin_nontemporal_load((const f32x4*)(s_in + sb + (size_t)(16 * wid + kk) * DV));
;     if (tid < DK) { const int col = h * DK + tid; float z = gb[col];
; #pragma unroll
;         for (int rr = 0; rr < RANK; ++rr) { float g = 0.f;
; #pragma unroll
;             for (int sp = 0; sp < NSP1; ++sp) g += GLRP[((size_t)sp * MPAD + row) * RANK + rr];
;             z += g * w2[rr * QKD + col]; }
;         smA[tid] = __expf(logsig_f(z) * (1.f / 16.f)); smK[tid] = prs_sum(PRS, s, 3584 + col); if (WITH_O) smQ[tid] = prs_sum(PRS, s, 3072 + col) * 0.08838834764831845f; }
;     const int dv4 = (tid & 63) * 4; const f32x4 v = prs_sum4(PRS, s, 4096 + h * DV + dv4);
;     ...
;         const float og = prs_sum(PRS, s, 5120 + h * DV + tid); Y[(size_t)row * DM + 1024 + h * DV + tid] = f2bf(oo * rstd * gn[h * DV + tid] * silu_f(og)); }
.LBB0_360:
	s_ashr_i32 s100, s55, 2
	s_mul_i32 s100, s100, 0x6400
	s_and_b32 s101, s55, 3
	s_lshl_b32 s101, s101, 10
	s_add_u32 s100, s100, s101
	s_add_u32 s98, s22, s100
	s_addc_u32 s99, s23, 0
	v_lshlrev_b32_e32 v196, 2, v121
	v_add_u32_e32 v196, 0x4000, v196
	v_and_b32_e32 v197, 0xff, v112
	v_lshlrev_b32_e32 v197, 2, v197
	v_add_u32_e32 v198, 0x5000, v197
	global_load_dwordx4 v[180:183], v196, s[98:99]
	global_load_dword v200, v198, s[98:99]
	s_add_u32 s100, s98, 0x320000
	s_addc_u32 s101, s99, 0
	global_load_dwordx4 v[184:187], v196, s[100:101]
	global_load_dword v201, v198, s[100:101]
	s_add_u32 s100, s98, 0x640000
	s_addc_u32 s101, s99, 0
	global_load_dwordx4 v[188:191], v196, s[100:101]
	global_load_dword v202, v198, s[100:101]
	s_add_u32 s100, s98, 0x960000
	s_addc_u32 s101, s99, 0
	global_load_dwordx4 v[192:195], v196, s[100:101]
	global_load_dword v203, v198, s[100:101]
	s_and_b32 s100, s55, 3
	s_lshl_b32 s100, s100, 10
	s_add_u32 s100, s2, s100
	s_addc_u32 s101, s3, 0
	global_load_dword v204, v197, s[100:101]
	v_lshl_add_u64 v[0:1], s[24:25], 0, v[114:115]
	v_add_co_u32_e32 v2, vcc, 0x1000, v0
	global_load_dwordx4 v[60:63], v[0:1], off nt
	global_load_dwordx4 v[56:59], v[0:1], off offset:1024 nt
	global_load_dwordx4 v[52:55], v[0:1], off offset:2048 nt
	global_load_dwordx4 v[48:51], v[0:1], off offset:3072 nt
	v_addc_co_u32_e32 v3, vcc, 0, v1, vcc
	global_load_dwordx4 v[44:47], v[2:3], off nt
	global_load_dwordx4 v[40:43], v[2:3], off offset:1024 nt
	global_load_dwordx4 v[36:39], v[2:3], off offset:2048 nt
	global_load_dwordx4 v[32:35], v[2:3], off offset:3072 nt
	v_add_co_u32_e32 v2, vcc, s59, v0
	s_ashr_i32 s8, s55, 2
	s_nop 0
	v_addc_co_u32_e32 v3, vcc, 0, v1, vcc
	v_add_co_u32_e32 v0, vcc, 0x3000, v0
	global_load_dwordx4 v[28:31], v[2:3], off nt
	global_load_dwordx4 v[24:27], v[2:3], off offset:1024 nt
	global_load_dwordx4 v[20:23], v[2:3], off offset:2048 nt
	global_load_dwordx4 v[16:19], v[2:3], off offset:3072 nt
	v_addc_co_u32_e32 v1, vcc, 0, v1, vcc
	global_load_dwordx4 v[12:15], v[0:1], off nt
	global_load_dwordx4 v[8:11], v[0:1], off offset:1024 nt
	global_load_dwordx4 v[4:7], v[0:1], off offset:2048 nt
	s_nop 0
	global_load_dwordx4 v[0:3], v[0:1], off offset:3072 nt
	s_mul_hi_i32 s49, s8, 0x6400
	s_mul_i32 s48, s8, 0x6400
	s_and_saveexec_b64 s[6:7], s[42:43]
	s_xor_b64 s[6:7], exec, s[6:7]
	s_or_saveexec_b64 s[52:53], s[6:7]
	s_and_b32 s6, s55, 3
	s_add_i32 s34, s8, 0x2000
	v_mov_b64_e32 v[72:73], s[48:49]
	s_xor_b64 exec, exec, s[52:53]
	s_cbranch_execz .LBB0_362
	s_ashr_i32 s35, s34, 31
	v_lshl_add_u32 v64, s6, 7, v112
	s_lshl_b64 s[46:47], s[34:35], 6
	v_lshlrev_b32_e32 v64, 2, v64
	s_add_u32 s46, s30, s46
	s_addc_u32 s47, s31, s47
	global_load_dword v65, v64, s[38:39]
	global_load_dwordx4 v[66:69], v169, s[46:47]
	global_load_dwordx4 v[74:77], v169, s[46:47] offset:16
	global_load_dwordx4 v[78:81], v169, s[46:47] offset:32
	global_load_dwordx4 v[82:85], v169, s[46:47] offset:48
	s_add_u32 s56, s46, 0x84000
	s_addc_u32 s57, s47, 0
	global_load_dwordx4 v[86:89], v169, s[56:57]
	global_load_dwordx4 v[90:93], v169, s[56:57] offset:16
	global_load_dwordx4 v[94:97], v169, s[56:57] offset:32
	global_load_dwordx4 v[98:101], v169, s[56:57] offset:48
	s_add_u32 s56, s46, 0x108000
	s_addc_u32 s57, s47, 0
	global_load_dwordx4 v[102:105], v169, s[56:57]
	global_load_dwordx4 v[106:109], v169, s[56:57] offset:16
	global_load_dwordx4 v[116:119], v169, s[56:57] offset:32
	global_load_dwordx4 v[126:129], v169, s[56:57] offset:48
	s_add_u32 s56, s46, 0x18c000
	s_addc_u32 s57, s47, 0
	global_load_dwordx4 v[130:133], v169, s[56:57]
	global_load_dwordx4 v[134:137], v169, s[56:57] offset:16
	global_load_dwordx4 v[138:141], v169, s[56:57] offset:32
	global_load_dwordx4 v[142:145], v169, s[56:57] offset:48
	global_load_dword v70, v64, s[4:5]
	global_load_dword v71, v64, s[4:5] offset:2048
	s_add_u32 s56, s4, 0x1000
	s_addc_u32 s57, s5, 0
	global_load_dword v110, v64, s[56:57]
	global_load_dword v111, v64, s[56:57] offset:2048
	s_add_u32 s56, s4, 0x2000
	s_addc_u32 s57, s5, 0
	global_load_dword v125, v64, s[56:57]
	global_load_dword v146, v64, s[56:57] offset:2048
	s_add_u32 s56, s4, 0x3000
	s_addc_u32 s57, s5, 0
	global_load_dword v147, v64, s[56:57]
	global_load_dword v148, v64, s[56:57] offset:2048
	s_add_u32 s56, s4, 0x4000
	s_addc_u32 s57, s5, 0
	global_load_dword v149, v64, s[56:57]
	global_load_dword v150, v64, s[56:57] offset:2048
	s_add_u32 s56, s4, 0x5000
	s_addc_u32 s57, s5, 0
	global_load_dword v151, v64, s[56:57]
	global_load_dword v152, v64, s[56:57] offset:2048
	s_add_u32 s56, s4, 0x6000
	s_addc_u32 s57, s5, 0
	global_load_dword v153, v64, s[56:57]
	global_load_dword v154, v64, s[56:57] offset:2048
	s_add_u32 s56, s4, 0x7000
	s_addc_u32 s57, s5, 0
	global_load_dword v155, v64, s[56:57]
	global_load_dword v156, v64, s[56:57] offset:2048
	s_mul_i32 s98, s8, 0x6400
	s_add_u32 s98, s22, s98
	s_addc_u32 s99, s23, 0
	s_add_u32 s98, s98, 0x3000
	s_addc_u32 s99, s99, 0
	global_load_dword v157, v64, s[98:99] offset:2048
	global_load_dword v161, v64, s[98:99]
	s_add_u32 s56, s98, 0x320000
	s_addc_u32 s57, s99, 0
	global_load_dword v158, v64, s[56:57] offset:2048
	global_load_dword v162, v64, s[56:57]
	s_add_u32 s56, s98, 0x640000
	s_addc_u32 s57, s99, 0
	global_load_dword v159, v64, s[56:57] offset:2048
	global_load_dword v163, v64, s[56:57]
	s_add_u32 s56, s98, 0x960000
	s_addc_u32 s57, s99, 0
	global_load_dword v160, v64, s[56:57] offset:2048
	global_load_dword v164, v64, s[56:57]
	s_waitcnt vmcnt(0)
; __device__ __forceinline__ float logsig_f(float z) { return fminf(z, 0.f) - __logf(1.f + __expf(-fabsf(z))); }
; template <bool WITH_O> __device__ __forceinline__ void gla_sample(LAS unsigned char* lds, int uidx, const float* PRS, const float* GLRP, const float* w2, const float* gb, const float* gn, ...
;     ...
;     if (tid < DK) { const int col = h * DK + tid; float z = gb[col];
; #pragma unroll
;         for (int rr = 0; rr < RANK; ++rr) { float g = 0.f;
; #pragma unroll
;             for (int sp = 0; sp < NSP1; ++sp) g += GLRP[((size_t)sp * MPAD + row) * RANK + rr];
;             z += g * w2[rr * QKD + col]; }
;         smA[tid] = __expf(logsig_f(z) * (1.f / 16.f)); smK[tid] = prs_sum(PRS, s, 3584 + col); if (WITH_O) smQ[tid] = prs_sum(PRS, s, 3072 + col) * 0.08838834764831845f; }
;     const int dv4 = (tid & 63) * 4; const f32x4 v = prs_sum4(PRS, s, 4096 + h * DV + dv4);
;     __syncthreads();
;     f32x4 o = {0.f, 0.f, 0.f, 0.f};
; #pragma unroll
;     for (int kk = 0; kk < 16; ++kk) { const int k = 16 * wid + kk; const f32x4 sn = S[kk] * smA[k] + v * smK[k]; if (!WITH_O || !DEFER_STATE) __builtin_nontemporal_store(sn, (f32x4*)(s_out + sb + (size_t)k * DV)); if (WITH_O) o += sn * smQ[k]; }
	v_add_f32_e32 v165, 0, v66
	v_add_f32_e32 v165, v165, v86
	v_add_f32_e32 v165, v165, v102
	v_add_f32_e32 v165, v165, v130
	v_fmac_f32_e32 v65, v165, v70
	v_add_f32_e32 v165, 0, v67
	v_add_f32_e32 v165, v165, v87
	v_add_f32_e32 v165, v165, v103
	v_add_f32_e32 v165, v165, v131
	v_fmac_f32_e32 v65, v165, v71
	v_add_f32_e32 v165, 0, v68
	v_add_f32_e32 v165, v165, v88
	v_add_f32_e32 v165, v165, v104
	v_add_f32_e32 v165, v165, v132
	v_fmac_f32_e32 v65, v165, v110
	v_add_f32_e32 v165, 0, v69
	v_add_f32_e32 v165, v165, v89
	v_add_f32_e32 v165, v165, v105
	v_add_f32_e32 v165, v165, v133
	v_fmac_f32_e32 v65, v165, v111
	v_add_f32_e32 v165, 0, v74
	v_add_f32_e32 v165, v165, v90
	v_add_f32_e32 v165, v165, v106
	v_add_f32_e32 v165, v165, v134
	v_fmac_f32_e32 v65, v165, v125
	v_add_f32_e32 v165, 0, v75
	v_add_f32_e32 v165, v165, v91
	v_add_f32_e32 v165, v165, v107
	v_add_f32_e32 v165, v165, v135
	v_fmac_f32_e32 v65, v165, v146
	v_add_f32_e32 v165, 0, v76
	v_add_f32_e32 v165, v165, v92
	v_add_f32_e32 v165, v165, v108
	v_add_f32_e32 v165, v165, v136
	v_fmac_f32_e32 v65, v165, v147
	v_add_f32_e32 v165, 0, v77
	v_add_f32_e32 v165, v165, v93
	v_add_f32_e32 v165, v165, v109
	v_add_f32_e32 v165, v165, v137
	v_fmac_f32_e32 v65, v165, v148
	v_add_f32_e32 v165, 0, v78
	v_add_f32_e32 v165, v165, v94
	v_add_f32_e32 v165, v165, v116
	v_add_f32_e32 v165, v165, v138
	v_fmac_f32_e32 v65, v165, v149
	v_add_f32_e32 v165, 0, v79
	v_add_f32_e32 v165, v165, v95
	v_add_f32_e32 v165, v165, v117
	v_add_f32_e32 v165, v165, v139
	v_fmac_f32_e32 v65, v165, v150
	v_add_f32_e32 v165, 0, v80
	v_add_f32_e32 v165, v165, v96
	v_add_f32_e32 v165, v165, v118
	v_add_f32_e32 v165, v165, v140
	v_fmac_f32_e32 v65, v165, v151
	v_add_f32_e32 v165, 0, v81
	v_add_f32_e32 v165, v165, v97
	v_add_f32_e32 v165, v165, v119
	v_add_f32_e32 v165, v165, v141
	v_fmac_f32_e32 v65, v165, v152
	v_add_f32_e32 v165, 0, v82
	v_add_f32_e32 v165, v165, v98
	v_add_f32_e32 v165, v165, v126
	v_add_f32_e32 v165, v165, v142
	v_fmac_f32_e32 v65, v165, v153
	v_add_f32_e32 v165, 0, v83
	v_add_f32_e32 v165, v165, v99
	v_add_f32_e32 v165, v165, v127
	v_add_f32_e32 v165, v165, v143
	v_fmac_f32_e32 v65, v165, v154
	v_add_f32_e32 v165, 0, v84
	v_add_f32_e32 v165, v165, v100
	v_add_f32_e32 v165, v165, v128
	v_add_f32_e32 v165, v165, v144
	v_fmac_f32_e32 v65, v165, v155
	v_add_f32_e32 v165, 0, v85
	v_add_f32_e32 v165, v165, v101
	v_add_f32_e32 v165, v165, v129
	v_add_f32_e32 v165, v165, v145
	v_fmac_f32_e32 v65, v165, v156
	v_mul_f32_e64 v166, |v65|, s17
	v_exp_f32_e32 v166, v166
	v_min_f32_e32 v167, 0, v65
	v_add_f32_e32 v166, 1.0, v166
	v_cmp_gt_f32_e32 vcc, s14, v166
	s_nop 1
	v_cndmask_b32_e64 v168, 0, 32, vcc
	v_ldexp_f32 v166, v166, v168
	v_log_f32_e32 v166, v166
	s_nop 0
	v_mul_f32_e32 v168, 0x3f317217, v166
	v_fma_f32 v168, v166, s18, -v168
	v_fmac_f32_e32 v168, 0x3377d1cf, v166
	v_fmac_f32_e32 v168, 0x3f317217, v166
	v_cmp_lt_f32_e64 s[46:47], |v166|, s19
	s_nop 1
	v_cndmask_b32_e64 v166, v166, v168, s[46:47]
	v_cndmask_b32_e32 v168, 0, v218, vcc
	v_sub_f32_e32 v166, v166, v168
	v_sub_f32_e32 v167, v167, v166
	v_mul_f32_e32 v167, 0x3d800000, v167
	v_mul_f32_e32 v167, 0x3fb8aa3b, v167
	v_exp_f32_e32 v178, v167
	v_add_f32_e32 v166, 0, v157
	v_add_f32_e32 v166, v166, v158
	v_add_f32_e32 v166, v166, v159
	v_add_f32_e32 v166, v166, v160
	v_add_f32_e32 v167, 0, v161
	v_add_f32_e32 v167, v167, v162
	v_add_f32_e32 v167, v167, v163
	v_add_f32_e32 v167, v167, v164
	v_mul_f32_e32 v167, 0x3db504f3, v167
	ds_write2st64_b32 v122, v178, v166 offset1:2
	ds_write_b32 v122, v167 offset:1024
.LBB0_362:
	s_or_b64 exec, exec, s[52:53]
	s_lshl_b32 s48, s6, 8
	v_or_b32_e32 v64, s48, v121
	v_lshlrev_b32_e32 v168, 2, v64
	v_mov_b32_e32 v78, s10
	s_mov_b32 s6, 0x4768000
	s_waitcnt lgkmcnt(0)
	s_barrier
	ds_read_b128 v[80:83], v78 offset:512
	s_waitcnt vmcnt(0)
	v_pk_add_f32 v[74:75], v[180:181], 0 op_sel_hi:[1,0]
	v_pk_add_f32 v[70:71], v[182:183], 0 op_sel_hi:[1,0]
	v_pk_add_f32 v[74:75], v[74:75], v[184:185]
	v_pk_add_f32 v[70:71], v[70:71], v[186:187]
	v_pk_add_f32 v[76:77], v[74:75], v[188:189]
	v_pk_add_f32 v[70:71], v[70:71], v[190:191]
	v_pk_add_f32 v[74:75], v[70:71], v[194:195]
	v_pk_add_f32 v[76:77], v[76:77], v[192:193]
	ds_read_b128 v[84:87], v78
	ds_read_b128 v[68:71], v78 offset:16
	ds_read_b128 v[64:67], v78 offset:32
	s_waitcnt lgkmcnt(3)
	v_pk_mul_f32 v[88:89], v[74:75], v[80:81] op_sel_hi:[1,0]
	v_pk_mul_f32 v[92:93], v[76:77], v[80:81] op_sel_hi:[1,0]
	s_waitcnt lgkmcnt(2)
	v_pk_fma_f32 v[90:91], v[62:63], v[84:85], v[88:89] op_sel_hi:[1,0,1]
	v_pk_fma_f32 v[88:89], v[60:61], v[84:85], v[92:93] op_sel_hi:[1,0,1]
	v_lshl_add_u64 v[60:61], s[28:29], 0, v[114:115]
	ds_read_b128 v[92:95], v78 offset:1024
	v_add_co_u32_e32 v96, vcc, s6, v60
	s_mov_b32 s6, 0x4769000
	s_nop 0
	v_addc_co_u32_e32 v97, vcc, 0, v61, vcc
	v_add_co_u32_e32 v62, vcc, s6, v60
	v_pk_mul_f32 v[98:99], v[74:75], v[80:81] op_sel:[0,1]
	s_nop 0
	v_addc_co_u32_e32 v63, vcc, 0, v61, vcc
	v_pk_mul_f32 v[80:81], v[76:77], v[80:81] op_sel:[0,1]
	global_store_dwordx4 v[62:63], v[88:91], off offset:-4096 nt
	v_pk_fma_f32 v[58:59], v[58:59], v[84:85], v[98:99] op_sel:[0,1,0]
	v_pk_fma_f32 v[56:57], v[56:57], v[84:85], v[80:81] op_sel:[0,1,0]
	s_waitcnt lgkmcnt(0)
; template <bool WITH_O> __device__ __forceinline__ void gla_sample(LAS unsigned char* lds, int uidx, const float* PRS, const float* GLRP, const float* w2, const float* gb, const float* gn, ...
;     ...
;     f32x4 o = {0.f, 0.f, 0.f, 0.f};
; #pragma unroll
;     for (int kk = 0; kk < 16; ++kk) { const int k = 16 * wid + kk; const f32x4 sn = S[kk] * smA[k] + v * smK[k]; if (!WITH_O || !DEFER_STATE) __builtin_nontemporal_store(sn, (f32x4*)(s_out + sb + (size_t)k * DV)); if (WITH_O) o += sn * smQ[k]; }
	v_pk_fma_f32 v[88:89], v[88:89], v[92:93], 0 op_sel_hi:[1,0,0]
	v_pk_mul_f32 v[80:81], v[74:75], v[82:83] op_sel_hi:[1,0]
	v_pk_mul_f32 v[84:85], v[76:77], v[82:83] op_sel_hi:[1,0]
	v_pk_fma_f32 v[90:91], v[90:91], v[92:93], 0 op_sel_hi:[1,0,0]
	global_store_dwordx4 v[96:97], v[56:59], off offset:1024 nt
	v_pk_fma_f32 v[54:55], v[54:55], v[86:87], v[80:81] op_sel_hi:[1,0,1]
	v_pk_fma_f32 v[52:53], v[52:53], v[86:87], v[84:85] op_sel_hi:[1,0,1]
	v_pk_fma_f32 v[56:57], v[56:57], v[92:93], v[88:89] op_sel:[0,1,0]
	v_pk_fma_f32 v[58:59], v[58:59], v[92:93], v[90:91] op_sel:[0,1,0]
	global_store_dwordx4 v[96:97], v[52:55], off offset:2048 nt
	v_mov_b32_e32 v80, v87
	s_mov_b32 s6, 0x476a000
	v_pk_fma_f32 v[52:53], v[52:53], v[94:95], v[56:57] op_sel_hi:[1,0,1]
	v_mov_b32_e32 v56, v83
	v_pk_fma_f32 v[54:55], v[54:55], v[94:95], v[58:59] op_sel_hi:[1,0,1]
	v_pk_mul_f32 v[58:59], v[74:75], v[56:57] op_sel_hi:[1,0]
	v_pk_mul_f32 v[56:57], v[76:77], v[56:57] op_sel_hi:[1,0]
	v_pk_fma_f32 v[50:51], v[50:51], v[80:81], v[58:59] op_sel_hi:[1,0,1]
	v_pk_fma_f32 v[48:49], v[48:49], v[80:81], v[56:57] op_sel_hi:[1,0,1]
	v_mov_b32_e32 v56, v95
	global_store_dwordx4 v[96:97], v[48:51], off offset:3072 nt
	v_pk_fma_f32 v[58:59], v[50:51], v[56:57], v[54:55] op_sel_hi:[1,0,1]
	v_pk_fma_f32 v[56:57], v[48:49], v[56:57], v[52:53] op_sel_hi:[1,0,1]
	ds_read_b128 v[48:51], v78 offset:528
	s_waitcnt lgkmcnt(0)
	v_pk_mul_f32 v[52:53], v[74:75], v[48:49] op_sel_hi:[1,0]
	v_pk_mul_f32 v[54:55], v[76:77], v[48:49] op_sel_hi:[1,0]
	v_pk_fma_f32 v[46:47], v[46:47], v[68:69], v[52:53] op_sel_hi:[1,0,1]
	v_pk_fma_f32 v[44:45], v[44:45], v[68:69], v[54:55] op_sel_hi:[1,0,1]
	ds_read_b128 v[52:55], v78 offset:1040
	global_store_dwordx4 v[62:63], v[44:47], off nt
	s_waitcnt lgkmcnt(0)
	s_nop 0
	v_pk_fma_f32 v[44:45], v[44:45], v[52:53], v[56:57] op_sel_hi:[1,0,1]
	v_pk_mul_f32 v[56:57], v[74:75], v[48:49] op_sel:[0,1]
	v_pk_mul_f32 v[48:49], v[76:77], v[48:49] op_sel:[0,1]
	v_pk_fma_f32 v[46:47], v[46:47], v[52:53], v[58:59] op_sel_hi:[1,0,1]
	v_pk_fma_f32 v[42:43], v[42:43], v[68:69], v[56:57] op_sel:[0,1,0]
	v_pk_fma_f32 v[40:41], v[40:41], v[68:69], v[48:49] op_sel:[0,1,0]
	global_store_dwordx4 v[62:63], v[40:43], off offset:1024 nt
	s_nop 1
	v_pk_fma_f32 v[42:43], v[42:43], v[52:53], v[46:47] op_sel:[0,1,0]
	v_pk_fma_f32 v[40:41], v[40:41], v[52:53], v[44:45] op_sel:[0,1,0]
	v_pk_mul_f32 v[44:45], v[74:75], v[50:51] op_sel_hi:[1,0]
	v_pk_mul_f32 v[46:47], v[76:77], v[50:51] op_sel_hi:[1,0]
	v_pk_fma_f32 v[38:39], v[38:39], v[70:71], v[44:45] op_sel_hi:[1,0,1]
	v_pk_fma_f32 v[36:37], v[36:37], v[70:71], v[46:47] op_sel_hi:[1,0,1]
	global_store_dwordx4 v[62:63], v[36:39], off offset:2048 nt
	v_mov_b32_e32 v44, v71
	s_nop 0
	v_pk_fma_f32 v[36:37], v[36:37], v[54:55], v[40:41] op_sel_hi:[1,0,1]
	v_mov_b32_e32 v40, v51
	v_pk_fma_f32 v[38:39], v[38:39], v[54:55], v[42:43] op_sel_hi:[1,0,1]
	v_pk_mul_f32 v[42:43], v[74:75], v[40:41] op_sel_hi:[1,0]
	v_pk_mul_f32 v[40:41], v[76:77], v[40:41] op_sel_hi:[1,0]
	v_pk_fma_f32 v[34:35], v[34:35], v[44:45], v[42:43] op_sel_hi:[1,0,1]
	v_pk_fma_f32 v[32:33], v[32:33], v[44:45], v[40:41] op_sel_hi:[1,0,1]
	v_mov_b32_e32 v40, v55
	global_store_dwordx4 v[62:63], v[32:35], off offset:3072 nt
	v_pk_fma_f32 v[44:45], v[34:35], v[40:41], v[38:39] op_sel_hi:[1,0,1]
	v_pk_fma_f32 v[46:47], v[32:33], v[40:41], v[36:37] op_sel_hi:[1,0,1]
	ds_read_b128 v[32:35], v78 offset:544
	s_waitcnt lgkmcnt(0)
	v_pk_mul_f32 v[36:37], v[74:75], v[32:33] op_sel_hi:[1,0]
	v_pk_mul_f32 v[40:41], v[76:77], v[32:33] op_sel_hi:[1,0]
	v_pk_fma_f32 v[38:39], v[30:31], v[64:65], v[36:37] op_sel_hi:[1,0,1]
	v_pk_fma_f32 v[36:37], v[28:29], v[64:65], v[40:41] op_sel_hi:[1,0,1]
	ds_read_b128 v[40:43], v78 offset:1056
	v_add_co_u32_e32 v30, vcc, s6, v60
	s_mov_b32 s6, 0x476b000
	s_nop 0
	v_addc_co_u32_e32 v31, vcc, 0, v61, vcc
	v_add_co_u32_e32 v28, vcc, s6, v60
	s_nop 1
	v_addc_co_u32_e32 v29, vcc, 0, v61, vcc
	global_store_dwordx4 v[28:29], v[36:39], off offset:-4096 nt
	s_waitcnt lgkmcnt(0)
; #define LAS __attribute__((address_space(3)))
; template <bool WITH_O> __device__ __forceinline__ void gla_sample(LAS unsigned char* lds, int uidx, const float* PRS, const float* GLRP, const float* w2, const float* gb, const float* gn, ...
;     ...
;     for (int kk = 0; kk < 16; ++kk) { const int k = 16 * wid + kk; const f32x4 sn = S[kk] * smA[k] + v * smK[k]; if (!WITH_O || !DEFER_STATE) __builtin_nontemporal_store(sn, (f32x4*)(s_out + sb + (size_t)k * DV)); if (WITH_O) o += sn * smQ[k]; }
;     if (!WITH_O) { __syncthreads(); return; }
;     *(LAS f32x4*)(smO + wid * 256 + dv4) = o;
;     __syncthreads();
;     float oo = 0.f;
;     if (tid < 256) {
; #pragma unroll
;         for (int w = 0; w < 8; ++w) oo += smO[w * 256 + tid];
;         const float ss = wave_sum(oo * oo); if (lane == 0) smR[wid] = ss; }
	s_nop 0
	v_pk_fma_f32 v[38:39], v[38:39], v[40:41], v[44:45] op_sel_hi:[1,0,1]
	v_pk_mul_f32 v[44:45], v[74:75], v[32:33] op_sel:[0,1]
	v_pk_mul_f32 v[32:33], v[76:77], v[32:33] op_sel:[0,1]
	v_pk_fma_f32 v[36:37], v[36:37], v[40:41], v[46:47] op_sel_hi:[1,0,1]
	v_pk_fma_f32 v[26:27], v[26:27], v[64:65], v[44:45] op_sel:[0,1,0]
	v_pk_fma_f32 v[24:25], v[24:25], v[64:65], v[32:33] op_sel:[0,1,0]
	global_store_dwordx4 v[30:31], v[24:27], off offset:1024 nt
	v_pk_mul_f32 v[32:33], v[74:75], v[34:35] op_sel_hi:[1,0]
	s_nop 0
	v_pk_fma_f32 v[24:25], v[24:25], v[40:41], v[36:37] op_sel:[0,1,0]
	v_pk_mul_f32 v[36:37], v[76:77], v[34:35] op_sel_hi:[1,0]
	v_pk_fma_f32 v[22:23], v[22:23], v[66:67], v[32:33] op_sel_hi:[1,0,1]
	v_pk_fma_f32 v[20:21], v[20:21], v[66:67], v[36:37] op_sel_hi:[1,0,1]
	v_pk_fma_f32 v[26:27], v[26:27], v[40:41], v[38:39] op_sel:[0,1,0]
	global_store_dwordx4 v[30:31], v[20:23], off offset:2048 nt
	v_pk_fma_f32 v[24:25], v[20:21], v[42:43], v[24:25] op_sel_hi:[1,0,1]
	v_mov_b32_e32 v32, v67
	v_mov_b32_e32 v20, v35
	v_pk_fma_f32 v[22:23], v[22:23], v[42:43], v[26:27] op_sel_hi:[1,0,1]
	v_pk_mul_f32 v[26:27], v[74:75], v[20:21] op_sel_hi:[1,0]
	v_pk_mul_f32 v[20:21], v[76:77], v[20:21] op_sel_hi:[1,0]
	v_pk_fma_f32 v[18:19], v[18:19], v[32:33], v[26:27] op_sel_hi:[1,0,1]
	v_pk_fma_f32 v[16:17], v[16:17], v[32:33], v[20:21] op_sel_hi:[1,0,1]
	global_store_dwordx4 v[30:31], v[16:19], off offset:3072 nt
	v_mov_b32_e32 v26, v43
	v_pk_fma_f32 v[20:21], v[18:19], v[26:27], v[22:23] op_sel_hi:[1,0,1]
	v_pk_fma_f32 v[22:23], v[16:17], v[26:27], v[24:25] op_sel_hi:[1,0,1]
	ds_read_b128 v[16:19], v78 offset:48
	ds_read_b128 v[24:27], v78 offset:560
	s_waitcnt lgkmcnt(0)
	v_pk_mul_f32 v[30:31], v[74:75], v[24:25] op_sel_hi:[1,0]
	v_pk_mul_f32 v[32:33], v[76:77], v[24:25] op_sel_hi:[1,0]
	v_pk_fma_f32 v[14:15], v[14:15], v[16:17], v[30:31] op_sel_hi:[1,0,1]
	v_pk_fma_f32 v[12:13], v[12:13], v[16:17], v[32:33] op_sel_hi:[1,0,1]
	ds_read_b128 v[30:33], v78 offset:1072
	global_store_dwordx4 v[28:29], v[12:15], off nt
	s_waitcnt lgkmcnt(0)
	s_nop 0
	v_pk_fma_f32 v[14:15], v[14:15], v[30:31], v[20:21] op_sel_hi:[1,0,1]
	v_pk_fma_f32 v[12:13], v[12:13], v[30:31], v[22:23] op_sel_hi:[1,0,1]
	v_pk_mul_f32 v[20:21], v[74:75], v[24:25] op_sel:[0,1]
	v_pk_mul_f32 v[22:23], v[76:77], v[24:25] op_sel:[0,1]
	v_pk_fma_f32 v[10:11], v[10:11], v[16:17], v[20:21] op_sel:[0,1,0]
	v_pk_fma_f32 v[8:9], v[8:9], v[16:17], v[22:23] op_sel:[0,1,0]
	global_store_dwordx4 v[28:29], v[8:11], off offset:1024 nt
	s_nop 1
	v_pk_fma_f32 v[10:11], v[10:11], v[30:31], v[14:15] op_sel:[0,1,0]
	v_pk_fma_f32 v[8:9], v[8:9], v[30:31], v[12:13] op_sel:[0,1,0]
	v_pk_mul_f32 v[12:13], v[74:75], v[26:27] op_sel_hi:[1,0]
	v_pk_mul_f32 v[14:15], v[76:77], v[26:27] op_sel_hi:[1,0]
	v_pk_fma_f32 v[6:7], v[6:7], v[18:19], v[12:13] op_sel_hi:[1,0,1]
	v_pk_fma_f32 v[4:5], v[4:5], v[18:19], v[14:15] op_sel_hi:[1,0,1]
	global_store_dwordx4 v[28:29], v[4:7], off offset:2048 nt
	v_mov_b32_e32 v12, v19
	s_nop 0
	v_pk_fma_f32 v[4:5], v[4:5], v[32:33], v[8:9] op_sel_hi:[1,0,1]
	v_mov_b32_e32 v8, v27
	v_pk_fma_f32 v[6:7], v[6:7], v[32:33], v[10:11] op_sel_hi:[1,0,1]
	v_pk_mul_f32 v[10:11], v[74:75], v[8:9] op_sel_hi:[1,0]
	v_pk_mul_f32 v[8:9], v[76:77], v[8:9] op_sel_hi:[1,0]
	v_pk_fma_f32 v[2:3], v[2:3], v[12:13], v[10:11] op_sel_hi:[1,0,1]
	v_pk_fma_f32 v[0:1], v[0:1], v[12:13], v[8:9] op_sel_hi:[1,0,1]
	v_mov_b32_e32 v8, v33
	global_store_dwordx4 v[28:29], v[0:3], off offset:3072 nt
	s_nop 1
	v_pk_fma_f32 v[2:3], v[2:3], v[8:9], v[6:7] op_sel_hi:[1,0,1]
	v_pk_fma_f32 v[0:1], v[0:1], v[8:9], v[4:5] op_sel_hi:[1,0,1]
	ds_write_b128 v123, v[0:3] offset:1536
	v_mov_b32_e32 v0, 0
	s_waitcnt lgkmcnt(0)
	s_barrier
	s_and_saveexec_b64 s[6:7], s[40:41]
	s_cbranch_execz .LBB0_366
	ds_read2st64_b32 v[0:1], v122 offset0:6 offset1:10
	v_xor_b32_e32 v3, 1, v211
	s_waitcnt lgkmcnt(0)
	v_add_f32_e32 v0, 0, v0
	v_add_f32_e32 v2, v0, v1
	ds_read2st64_b32 v[0:1], v122 offset0:14 offset1:18
	s_waitcnt lgkmcnt(0)
	v_add_f32_e32 v0, v2, v0
	v_add_f32_e32 v2, v0, v1
	ds_read2st64_b32 v[0:1], v122 offset0:22 offset1:26
	s_waitcnt lgkmcnt(0)
	v_add_f32_e32 v0, v2, v0
	v_add_f32_e32 v2, v0, v1
	ds_read2st64_b32 v[0:1], v122 offset0:30 offset1:34
	s_waitcnt lgkmcnt(0)
	v_add_f32_e32 v0, v2, v0
	v_and_b32_e32 v2, 64, v211
	v_add_u32_e32 v2, 64, v2
	v_cmp_lt_i32_e32 vcc, v3, v2
	v_add_f32_e32 v0, v0, v1
	v_mul_f32_e32 v1, v0, v0
	v_cndmask_b32_e32 v3, v211, v3, vcc
	v_lshlrev_b32_e32 v3, 2, v3
	ds_bpermute_b32 v1, v3, v1
	v_xor_b32_e32 v3, 2, v211
	v_cmp_lt_i32_e32 vcc, v3, v2
	s_waitcnt lgkmcnt(0)
	v_fmac_f32_e32 v1, v0, v0
	v_cndmask_b32_e32 v3, v211, v3, vcc
	v_lshlrev_b32_e32 v3, 2, v3
	ds_bpermute_b32 v3, v3, v1
	s_waitcnt lgkmcnt(0)
	v_add_f32_e32 v1, v1, v3
	v_xor_b32_e32 v3, 4, v211
	v_cmp_lt_i32_e32 vcc, v3, v2
	s_nop 1
	v_cndmask_b32_e32 v3, v211, v3, vcc
	v_lshlrev_b32_e32 v3, 2, v3
	ds_bpermute_b32 v3, v3, v1
	s_waitcnt lgkmcnt(0)
	v_add_f32_e32 v1, v1, v3
	v_xor_b32_e32 v3, 8, v211
	v_cmp_lt_i32_e32 vcc, v3, v2
	s_nop 1
	v_cndmask_b32_e32 v3, v211, v3, vcc
	v_lshlrev_b32_e32 v3, 2, v3
	ds_bpermute_b32 v3, v3, v1
	s_waitcnt lgkmcnt(0)
	v_add_f32_e32 v1, v1, v3
	v_xor_b32_e32 v3, 16, v211
	v_cmp_lt_i32_e32 vcc, v3, v2
	s_nop 1
	v_cndmask_b32_e32 v3, v211, v3, vcc
	v_lshlrev_b32_e32 v3, 2, v3
	ds_bpermute_b32 v3, v3, v1
	s_waitcnt lgkmcnt(0)
	v_add_f32_e32 v1, v1, v3
	v_xor_b32_e32 v3, 32, v211
	v_cmp_lt_i32_e32 vcc, v3, v2
	s_nop 1
	v_cndmask_b32_e32 v2, v211, v3, vcc
	v_lshlrev_b32_e32 v2, 2, v2
	ds_bpermute_b32 v2, v2, v1
	s_and_saveexec_b64 s[8:9], s[44:45]
	s_cbranch_execz .LBB0_365
	s_waitcnt lgkmcnt(0)
	v_add_f32_e32 v1, v1, v2
	v_mov_b32_e32 v2, s54
	ds_write_b32 v2, v1 offset:9728

; __device__ __forceinline__ bf16_t f2bf(float f) { return (bf16_t)(cvt_pk_bf16(f, 0.f) & 0xffffu); }
; __device__ __forceinline__ float silu_f(float x) { return x * __builtin_amdgcn_rcpf(1.f + __expf(-x)); }
; template <bool WITH_O> __device__ __forceinline__ void gla_sample(LAS unsigned char* lds, int uidx, const float* PRS, const float* GLRP, const float* w2, const float* gb, const float* gn, ...
;     ...
;     if (tid < 256) { const float tot = (smR[0] + smR[1]) + (smR[2] + smR[3]); const float rstd = rsqrtf(tot * (1.f / DV) + EPS);
;         const float og = prs_sum(PRS, s, 5120 + h * DV + tid); Y[(size_t)row * DM + 1024 + h * DV + tid] = f2bf(oo * rstd * gn[h * DV + tid] * silu_f(og)); }
.LBB0_366:
	s_or_b64 exec, exec, s[6:7]
	s_waitcnt lgkmcnt(0)
	s_barrier
	s_and_saveexec_b64 s[46:47], s[40:41]
	s_cbranch_execz .LBB0_359
	ds_read_b128 v[2:5], v169 offset:9728
	s_ashr_i32 s35, s34, 31
	s_lshl_b64 s[6:7], s[34:35], 12
	s_add_u32 s6, s50, s6
	s_addc_u32 s7, s51, s7
	s_waitcnt lgkmcnt(0)
	v_mov_b32_e32 v6, v3
	v_mov_b32_e32 v7, v4
	v_mov_b32_e32 v3, v5
	v_pk_add_f32 v[2:3], v[6:7], v[2:3]
	s_lshl_b32 s8, s48, 1
	v_add_f32_e32 v1, v2, v3
	v_fmamk_f32 v1, v1, 0x3b800000, v212
	v_cmp_gt_f32_e32 vcc, s14, v1
	v_mul_f32_e32 v2, 0x4b800000, v1
	s_add_u32 s6, s6, s8
	v_cndmask_b32_e32 v1, v1, v2, vcc
	v_rsq_f32_e32 v1, v1
	s_addc_u32 s7, s7, 0
	v_mul_f32_e32 v2, 0x45800000, v1
	v_cndmask_b32_e32 v1, v1, v2, vcc
	v_mul_f32_e32 v3, v0, v1
	v_add_f32_e32 v6, 0, v200
	v_add_f32_e32 v6, v6, v201
	v_add_f32_e32 v4, v6, v202
	v_add_f32_e32 v2, v4, v203
	v_mov_b32_e32 v1, v204
	v_mul_f32_e32 v0, 0xbfb8aa3b, v2
	v_exp_f32_e32 v0, v0
	s_nop 0
	v_add_f32_e32 v0, 1.0, v0
	v_rcp_f32_e32 v0, v0
	s_nop 0
	v_pk_mul_f32 v[0:1], v[2:3], v[0:1]
	s_nop 0
	v_mul_f32_e32 v0, v0, v1
	v_cvt_pk_bf16_f32 v2, v0, v169
	v_lshl_add_u64 v[0:1], v[112:113], 1, s[6:7]
	v_add_co_u32_e32 v0, vcc, 0x18c84000, v0
	s_nop 1
	v_addc_co_u32_e32 v1, vcc, 0, v1, vcc
	global_store_short v[0:1], v2, off offset:2048
	s_branch .LBB0_359
